# hgrn_scan: last block re-loads in-bounds data instead of prefetching past the arrays (otherwise same as previous version)
# baseline (speedup 1.0000x reference)
; #define TIDX launder((int)threadIdx.x)
; DI float bf2f(bf16_t v) { return __uint_as_float(((unsigned)v) << 16); }
; DI bf16_t f2bf(float x) { return (bf16_t)(pk2(x, 0.f) & 0xffffu); }
; DI void hgrn_scan(const Params& p) {
;     ...
;   for (int idx = blockIdx.x * NTH + TIDX; idx < 16 * 128 * 128; idx += gridDim.x * NTH) {
;     const int k = idx & 127, v = (idx >> 7) & 127, bh = idx >> 14;
;     float S = 0.f;
; #pragma unroll 8
;     for (int c = 0; c < 64; ++c) {
;       const size_t o = (((size_t)bh * 64 + c) * 128 + v) * 128 + k;
;       ST[o] = f2bf(S);
;       S = DL[((size_t)bh * 64 + c) * 128 + k] * S + bf2f(U[o]);
;     }
;   }
.Lscan_blk:
	s_add_u32 s6, s10, 0x351c5000
	s_addc_u32 s7, s11, 0
	s_add_u32 s8, s10, 0x31145000
	s_addc_u32 s9, s11, 0
	global_load_ushort v36, v6, s[8:9]
	global_load_dword v44, v10, s[6:7]
	s_add_u32 s8, s10, 0x3114d000
	s_addc_u32 s9, s11, 0
	global_load_ushort v37, v6, s[8:9]
	global_load_dword v45, v10, s[6:7] offset:512
	s_add_u32 s8, s10, 0x31155000
	s_addc_u32 s9, s11, 0
	global_load_ushort v38, v6, s[8:9]
	global_load_dword v46, v10, s[6:7] offset:1024
	s_add_u32 s8, s10, 0x3115d000
	s_addc_u32 s9, s11, 0
	global_load_ushort v39, v6, s[8:9]
	global_load_dword v47, v10, s[6:7] offset:1536
	s_add_u32 s8, s10, 0x31165000
	s_addc_u32 s9, s11, 0
	global_load_ushort v40, v6, s[8:9]
	global_load_dword v48, v10, s[6:7] offset:2048
	s_add_u32 s8, s10, 0x3116d000
	s_addc_u32 s9, s11, 0
	global_load_ushort v41, v6, s[8:9]
	global_load_dword v49, v10, s[6:7] offset:2560
	s_add_u32 s8, s10, 0x31175000
	s_addc_u32 s9, s11, 0
	global_load_ushort v42, v6, s[8:9]
	global_load_dword v50, v10, s[6:7] offset:3072
	s_add_u32 s8, s10, 0x3117d000
	s_addc_u32 s9, s11, 0
	global_load_ushort v43, v6, s[8:9]
	global_load_dword v51, v10, s[6:7] offset:3584
	v_cvt_pk_bf16_f32 v16, v5, s0
	s_add_u32 s8, s10, 0x29145000
	s_addc_u32 s9, s11, 0
	global_store_short v12, v16, s[8:9]
	s_waitcnt vmcnt(31)
	v_lshlrev_b32_e32 v18, 16, v20
	v_fmac_f32_e32 v18, v5, v28
	v_cvt_pk_bf16_f32 v16, v18, s0
	s_add_u32 s8, s10, 0x2914d000
	s_addc_u32 s9, s11, 0
	global_store_short v12, v16, s[8:9]
	s_waitcnt vmcnt(30)
	v_lshlrev_b32_e32 v19, 16, v21
	v_fmac_f32_e32 v19, v18, v29
	v_cvt_pk_bf16_f32 v16, v19, s0
	s_add_u32 s8, s10, 0x29155000
	s_addc_u32 s9, s11, 0
	global_store_short v12, v16, s[8:9]
	s_waitcnt vmcnt(29)
	v_lshlrev_b32_e32 v18, 16, v22
	v_fmac_f32_e32 v18, v19, v30
	v_cvt_pk_bf16_f32 v16, v18, s0
	s_add_u32 s8, s10, 0x2915d000
	s_addc_u32 s9, s11, 0
	global_store_short v12, v16, s[8:9]
	s_waitcnt vmcnt(28)
	v_lshlrev_b32_e32 v19, 16, v23
	v_fmac_f32_e32 v19, v18, v31
	v_cvt_pk_bf16_f32 v16, v19, s0
	s_add_u32 s8, s10, 0x29165000
	s_addc_u32 s9, s11, 0
	global_store_short v12, v16, s[8:9]
	s_waitcnt vmcnt(27)
	v_lshlrev_b32_e32 v18, 16, v24
	v_fmac_f32_e32 v18, v19, v32
	v_cvt_pk_bf16_f32 v16, v18, s0
	s_add_u32 s8, s10, 0x2916d000
	s_addc_u32 s9, s11, 0
	global_store_short v12, v16, s[8:9]
	s_waitcnt vmcnt(26)
	v_lshlrev_b32_e32 v19, 16, v25
	v_fmac_f32_e32 v19, v18, v33
	v_cvt_pk_bf16_f32 v16, v19, s0
	s_add_u32 s8, s10, 0x29175000
	s_addc_u32 s9, s11, 0
	global_store_short v12, v16, s[8:9]
	s_waitcnt vmcnt(25)
	v_lshlrev_b32_e32 v18, 16, v26
	v_fmac_f32_e32 v18, v19, v34
	v_cvt_pk_bf16_f32 v16, v18, s0
	s_add_u32 s8, s10, 0x2917d000
	s_addc_u32 s9, s11, 0
	global_store_short v12, v16, s[8:9]
	s_waitcnt vmcnt(24)
	v_lshlrev_b32_e32 v5, 16, v27
	v_fmac_f32_e32 v5, v18, v35
	v_mov_b32_e32 v12, v6
	s_cmp_lg_u32 s4, 16
	s_cselect_b32 s6, 0x40000, 0
	s_cselect_b32 s7, 0x1000, 0
	v_add_u32_e32 v6, s6, v6
	v_add_u32_e32 v10, s7, v10
	s_add_u32 s6, s10, 0x351c5000
	s_addc_u32 s7, s11, 0
	s_add_u32 s8, s10, 0x31145000
	s_addc_u32 s9, s11, 0
	global_load_ushort v20, v6, s[8:9]
	global_load_dword v28, v10, s[6:7]
	s_add_u32 s8, s10, 0x3114d000
	s_addc_u32 s9, s11, 0
	global_load_ushort v21, v6, s[8:9]
	global_load_dword v29, v10, s[6:7] offset:512
	s_add_u32 s8, s10, 0x31155000
	s_addc_u32 s9, s11, 0
	global_load_ushort v22, v6, s[8:9]
	global_load_dword v30, v10, s[6:7] offset:1024
	s_add_u32 s8, s10, 0x3115d000
	s_addc_u32 s9, s11, 0
	global_load_ushort v23, v6, s[8:9]
	global_load_dword v31, v10, s[6:7] offset:1536
	s_add_u32 s8, s10, 0x31165000
	s_addc_u32 s9, s11, 0
	global_load_ushort v24, v6, s[8:9]
	global_load_dword v32, v10, s[6:7] offset:2048
	s_add_u32 s8, s10, 0x3116d000
	s_addc_u32 s9, s11, 0
	global_load_ushort v25, v6, s[8:9]
	global_load_dword v33, v10, s[6:7] offset:2560
	s_add_u32 s8, s10, 0x31175000
	s_addc_u32 s9, s11, 0
	global_load_ushort v26, v6, s[8:9]
	global_load_dword v34, v10, s[6:7] offset:3072
	s_add_u32 s8, s10, 0x3117d000
	s_addc_u32 s9, s11, 0
	global_load_ushort v27, v6, s[8:9]
	global_load_dword v35, v10, s[6:7] offset:3584
	v_cvt_pk_bf16_f32 v16, v5, s0
	s_add_u32 s8, s10, 0x29145000
	s_addc_u32 s9, s11, 0
	global_store_short v12, v16, s[8:9]
	s_waitcnt vmcnt(39)
	v_lshlrev_b32_e32 v18, 16, v36
	v_fmac_f32_e32 v18, v5, v44
	v_cvt_pk_bf16_f32 v16, v18, s0
	s_add_u32 s8, s10, 0x2914d000
	s_addc_u32 s9, s11, 0
	global_store_short v12, v16, s[8:9]
	s_waitcnt vmcnt(38)
	v_lshlrev_b32_e32 v19, 16, v37
	v_fmac_f32_e32 v19, v18, v45
	v_cvt_pk_bf16_f32 v16, v19, s0
	s_add_u32 s8, s10, 0x29155000
	s_addc_u32 s9, s11, 0
	global_store_short v12, v16, s[8:9]
	s_waitcnt vmcnt(37)
	v_lshlrev_b32_e32 v18, 16, v38
	v_fmac_f32_e32 v18, v19, v46
	v_cvt_pk_bf16_f32 v16, v18, s0
	s_add_u32 s8, s10, 0x2915d000
	s_addc_u32 s9, s11, 0
	global_store_short v12, v16, s[8:9]
	s_waitcnt vmcnt(36)
	v_lshlrev_b32_e32 v19, 16, v39
	v_fmac_f32_e32 v19, v18, v47
	v_cvt_pk_bf16_f32 v16, v19, s0
	s_add_u32 s8, s10, 0x29165000
	s_addc_u32 s9, s11, 0
	global_store_short v12, v16, s[8:9]
	s_waitcnt vmcnt(35)
	v_lshlrev_b32_e32 v18, 16, v40
	v_fmac_f32_e32 v18, v19, v48
	v_cvt_pk_bf16_f32 v16, v18, s0
	s_add_u32 s8, s10, 0x2916d000
	s_addc_u32 s9, s11, 0
	global_store_short v12, v16, s[8:9]
	s_waitcnt vmcnt(34)
	v_lshlrev_b32_e32 v19, 16, v41
	v_fmac_f32_e32 v19, v18, v49
	v_cvt_pk_bf16_f32 v16, v19, s0
	s_add_u32 s8, s10, 0x29175000
	s_addc_u32 s9, s11, 0
	global_store_short v12, v16, s[8:9]
	s_waitcnt vmcnt(33)
	v_lshlrev_b32_e32 v18, 16, v42
	v_fmac_f32_e32 v18, v19, v50
	v_cvt_pk_bf16_f32 v16, v18, s0
	s_add_u32 s8, s10, 0x2917d000
	s_addc_u32 s9, s11, 0
	global_store_short v12, v16, s[8:9]
	s_waitcnt vmcnt(32)
	v_lshlrev_b32_e32 v5, 16, v43
	v_fmac_f32_e32 v5, v18, v51
	v_mov_b32_e32 v12, v6
	v_add_u32_e32 v6, 0x40000, v6
	v_add_u32_e32 v10, 0x1000, v10
	s_add_i32 s4, s4, -16
	s_cmp_eq_u32 s4, 0
	s_cbranch_scc0 .Lscan_blk
	s_waitcnt vmcnt(0)
	v_readlane_b32 s4, v250, 10
	s_nop 1
	v_add_u32_e32 v3, s4, v3
	s_mov_b32 s4, 0x3ffff
	v_cmp_lt_i32_e32 vcc, s4, v3
	s_or_b64 s[2:3], vcc, s[2:3]
	s_andn2_b64 exec, exec, s[2:3]
	s_cbranch_execnz .LBB0_290
